# phase 4 branch-projection epilogue: 16 gate-row loads hoisted ahead of the 8 row iterations (straight-line, LDS reads double-buffered, waits count younger loads only)
# baseline (speedup 1.0000x reference)
.Lp5_nowait:
.LBB0_782:
	v_ashrrev_i32_e32 v3, 31, v2
	v_lshlrev_b64 v[4:5], 10, v[2:3]
	v_lshl_add_u64 v[4:5], v[4:5], 0, v[0:1]
	v_lshlrev_b64 v[4:5], 1, v[4:5]
	s_mov_b64 s[6:7], 0x8000
	v_lshl_add_u64 v[12:13], s[0:1], 0, v[4:5]
	v_lshl_add_u64 v[14:15], s[60:61], 0, v[4:5]
	v_lshl_add_u64 v[20:21], s[60:61], 0, v[4:5]
	ds_read_b128 v[208:211], v151 offset:32768
	ds_read_b128 v[212:215], v151
	global_load_dwordx4 v[22:25], v[12:13], off
	global_load_dwordx4 v[26:29], v[14:15], off
	v_lshl_add_u64 v[12:13], v[12:13], 0, s[6:7]
	v_lshl_add_u64 v[14:15], v[14:15], 0, s[6:7]
	global_load_dwordx4 v[30:33], v[12:13], off
	global_load_dwordx4 v[34:37], v[14:15], off
	v_lshl_add_u64 v[12:13], v[12:13], 0, s[6:7]
	v_lshl_add_u64 v[14:15], v[14:15], 0, s[6:7]
	global_load_dwordx4 v[38:41], v[12:13], off
	global_load_dwordx4 v[42:45], v[14:15], off
	v_lshl_add_u64 v[12:13], v[12:13], 0, s[6:7]
	v_lshl_add_u64 v[14:15], v[14:15], 0, s[6:7]
	global_load_dwordx4 v[46:49], v[12:13], off
	global_load_dwordx4 v[50:53], v[14:15], off
	v_lshl_add_u64 v[12:13], v[12:13], 0, s[6:7]
	v_lshl_add_u64 v[14:15], v[14:15], 0, s[6:7]
	global_load_dwordx4 v[54:57], v[12:13], off
	global_load_dwordx4 v[58:61], v[14:15], off
	v_lshl_add_u64 v[12:13], v[12:13], 0, s[6:7]
	v_lshl_add_u64 v[14:15], v[14:15], 0, s[6:7]
	global_load_dwordx4 v[90:93], v[12:13], off
	global_load_dwordx4 v[94:97], v[14:15], off
	v_lshl_add_u64 v[12:13], v[12:13], 0, s[6:7]
	v_lshl_add_u64 v[14:15], v[14:15], 0, s[6:7]
	global_load_dwordx4 v[98:101], v[12:13], off
	global_load_dwordx4 v[102:105], v[14:15], off
	v_lshl_add_u64 v[12:13], v[12:13], 0, s[6:7]
	v_lshl_add_u64 v[14:15], v[14:15], 0, s[6:7]
	global_load_dwordx4 v[200:203], v[12:13], off
	global_load_dwordx4 v[204:207], v[14:15], off
	ds_read_b128 v[240:243], v151 offset:36864
	ds_read_b128 v[244:247], v151 offset:4096
	s_waitcnt vmcnt(14) lgkmcnt(2)
	v_pk_mul_f16 v4, v208, v22
	v_pk_mul_f16 v5, v209, v23
	v_pk_mul_f16 v6, v210, v24
	v_pk_mul_f16 v7, v211, v25
	v_pk_fma_f16 v4, v212, v26, v4
	v_pk_fma_f16 v5, v213, v27, v5
	v_pk_fma_f16 v6, v214, v28, v6
	v_pk_fma_f16 v7, v215, v29, v7
	global_store_dwordx4 v[20:21], v[4:7], off
	v_lshl_add_u64 v[20:21], v[20:21], 0, s[6:7]
	ds_read_b128 v[208:211], v151 offset:40960
	ds_read_b128 v[212:215], v151 offset:8192
	s_waitcnt vmcnt(12) lgkmcnt(2)
	v_pk_mul_f16 v8, v240, v30
	v_pk_mul_f16 v9, v241, v31
	v_pk_mul_f16 v10, v242, v32
	v_pk_mul_f16 v11, v243, v33
	v_pk_fma_f16 v8, v244, v34, v8
	v_pk_fma_f16 v9, v245, v35, v9
	v_pk_fma_f16 v10, v246, v36, v10
	v_pk_fma_f16 v11, v247, v37, v11
	global_store_dwordx4 v[20:21], v[8:11], off
	v_lshl_add_u64 v[20:21], v[20:21], 0, s[6:7]
	ds_read_b128 v[240:243], v151 offset:45056
	ds_read_b128 v[244:247], v151 offset:12288
	s_waitcnt vmcnt(10) lgkmcnt(2)
	v_pk_mul_f16 v4, v208, v38
	v_pk_mul_f16 v5, v209, v39
	v_pk_mul_f16 v6, v210, v40
	v_pk_mul_f16 v7, v211, v41
	v_pk_fma_f16 v4, v212, v42, v4
	v_pk_fma_f16 v5, v213, v43, v5
	v_pk_fma_f16 v6, v214, v44, v6
	v_pk_fma_f16 v7, v215, v45, v7
	global_store_dwordx4 v[20:21], v[4:7], off
	v_lshl_add_u64 v[20:21], v[20:21], 0, s[6:7]
	ds_read_b128 v[208:211], v151 offset:49152
	ds_read_b128 v[212:215], v151 offset:16384
	s_waitcnt vmcnt(8) lgkmcnt(2)
	v_pk_mul_f16 v8, v240, v46
	v_pk_mul_f16 v9, v241, v47
	v_pk_mul_f16 v10, v242, v48
	v_pk_mul_f16 v11, v243, v49
	v_pk_fma_f16 v8, v244, v50, v8
	v_pk_fma_f16 v9, v245, v51, v9
	v_pk_fma_f16 v10, v246, v52, v10
	v_pk_fma_f16 v11, v247, v53, v11
	global_store_dwordx4 v[20:21], v[8:11], off
	v_lshl_add_u64 v[20:21], v[20:21], 0, s[6:7]
	ds_read_b128 v[240:243], v151 offset:53248
	ds_read_b128 v[244:247], v151 offset:20480
	s_waitcnt vmcnt(6) lgkmcnt(2)
	v_pk_mul_f16 v4, v208, v54
	v_pk_mul_f16 v5, v209, v55
	v_pk_mul_f16 v6, v210, v56
	v_pk_mul_f16 v7, v211, v57
	v_pk_fma_f16 v4, v212, v58, v4
	v_pk_fma_f16 v5, v213, v59, v5
	v_pk_fma_f16 v6, v214, v60, v6
	v_pk_fma_f16 v7, v215, v61, v7
	global_store_dwordx4 v[20:21], v[4:7], off
	v_lshl_add_u64 v[20:21], v[20:21], 0, s[6:7]
	ds_read_b128 v[208:211], v151 offset:57344
	ds_read_b128 v[212:215], v151 offset:24576
	s_waitcnt vmcnt(4) lgkmcnt(2)
	v_pk_mul_f16 v8, v240, v90
	v_pk_mul_f16 v9, v241, v91
	v_pk_mul_f16 v10, v242, v92
	v_pk_mul_f16 v11, v243, v93
	v_pk_fma_f16 v8, v244, v94, v8
	v_pk_fma_f16 v9, v245, v95, v9
	v_pk_fma_f16 v10, v246, v96, v10
	v_pk_fma_f16 v11, v247, v97, v11
	global_store_dwordx4 v[20:21], v[8:11], off
	v_lshl_add_u64 v[20:21], v[20:21], 0, s[6:7]
	ds_read_b128 v[240:243], v151 offset:61440
	ds_read_b128 v[244:247], v151 offset:28672
	s_waitcnt vmcnt(2) lgkmcnt(2)
	v_pk_mul_f16 v4, v208, v98
	v_pk_mul_f16 v5, v209, v99
	v_pk_mul_f16 v6, v210, v100
	v_pk_mul_f16 v7, v211, v101
	v_pk_fma_f16 v4, v212, v102, v4
	v_pk_fma_f16 v5, v213, v103, v5
	v_pk_fma_f16 v6, v214, v104, v6
	v_pk_fma_f16 v7, v215, v105, v7
	global_store_dwordx4 v[20:21], v[4:7], off
	v_lshl_add_u64 v[20:21], v[20:21], 0, s[6:7]
	s_waitcnt vmcnt(0) lgkmcnt(0)
	v_pk_mul_f16 v8, v240, v200
	v_pk_mul_f16 v9, v241, v201
	v_pk_mul_f16 v10, v242, v202
	v_pk_mul_f16 v11, v243, v203
	v_pk_fma_f16 v8, v244, v204, v8
	v_pk_fma_f16 v9, v245, v205, v9
	v_pk_fma_f16 v10, v246, v206, v10
	v_pk_fma_f16 v11, v247, v207, v11
	global_store_dwordx4 v[20:21], v[8:11], off
	s_cmp_eq_u32 s84, 0x200
	s_cbranch_scc0 .Lp5_orig
	s_barrier
	s_lshr_b32 s6, s2, 3
	s_and_b32 s6, s6, 7
	s_mul_i32 s6, s6, 0x85
	s_and_b32 s7, s2, 7
	s_add_i32 s8, s6, s7
	s_addk_i32 s8, 0x80
	s_cmp_eq_u32 s20, s8
	s_cbranch_scc1 .LBB0_784
	s_add_i32 s20, s20, 64
	v_add_u32_e32 v120, 0x2000, v120
	v_add_u32_e32 v121, 0x2000, v121
	v_add_u32_e32 v122, 0x2000, v122
	v_add_u32_e32 v123, 0x2000, v123
	v_add_u32_e32 v168, 0x2000, v168
	s_add_i32 s9, s6, 0x85
	s_cmp_lt_i32 s20, s9
	s_cbranch_scc0 .Lp5_xend
	s_cmp_eq_u32 s20, s8
	s_cbranch_scc0 .LBB0_773
	s_branch .LBB0_784
